# one static priority raise for waves 4-7 across the whole m4 phase (both attention items and the ssd_s3 item), reset at the phase end
# baseline (speedup 1.0000x reference)
.LBB0_1254:
	s_andn2_b64 vcc, exec, s[6:7]
	s_cbranch_vccnz .LBB0_2256
	s_mov_b64 s[4:5], s[0:1]
	s_load_dwordx2 s[90:91], s[4:5], 0xd8
	v_readfirstlane_b32 s2, v180
	s_ashr_i32 s2, s2, 6
	s_cmp_ge_u32 s2, 4
	s_cbranch_scc0 .Lm4_prio_skip
	s_setprio 2
.Lm4_prio_skip:
	v_and_b32_e32 v181, 63, v180
	s_mul_i32 s18, s2, 0x4500
	v_or_b32_e32 v221, 0xffffffc0, v181
	v_lshlrev_b32_e32 v222, 2, v181
	s_add_i32 s96, s18, 0
	v_add_u32_e32 v2, s96, v222
	s_mov_b64 s[6:7], 0
	v_mov_b32_e32 v3, v221

.LBB0_2363:
	s_setprio 0
	s_mov_b64 s[8:9], s[0:1]
	s_waitcnt vmcnt(0) lgkmcnt(0)
	s_add_i32 s2, s51, 4
	s_barrier
	s_mov_b64 s[6:7], exec
	v_readlane_b32 s4, v243, 4
	v_readlane_b32 s5, v243, 5
	s_and_b64 s[4:5], s[6:7], s[4:5]
	s_mov_b64 exec, s[4:5]
	s_cbranch_execz .LBB0_2380
	s_load_dwordx2 s[8:9], s[8:9], 0xd8
	buffer_wbl2 sc1
	s_waitcnt vmcnt(0) lgkmcnt(0)
	s_waitcnt vmcnt(0)
	v_readlane_b32 s10, v242, 9
	v_readlane_b32 s11, v242, 10
	s_add_u32 s12, s8, 0xe0000
	s_addc_u32 s13, s9, 0
	s_and_saveexec_b64 s[4:5], s[10:11]
	s_xor_b64 s[10:11], exec, s[4:5]
	s_cbranch_execz .LBB0_2369
	s_mov_b64 s[16:17], exec
	v_mbcnt_lo_u32_b32 v2, s16, 0
	v_mbcnt_hi_u32_b32 v2, s17, v2
	v_cmp_eq_u32_e32 vcc, 0, v2
	s_and_saveexec_b64 s[14:15], vcc
	s_cbranch_execz .LBB0_2367
	s_bcnt1_i32_b64 s4, s[16:17]
	v_mov_b32_e32 v2, s4
	global_atomic_add v11, v2, s[12:13]
